# v20 + mlaprep token loop software-pipelined: next token's 13 loads issued before the current token's reductions
# baseline (speedup 1.0000x reference)
; DI float bf2f(bft h) { return __uint_as_float(((unsigned)h) << 16); }
; DI void phase_mlaprep(const Params& p) {
;   int tix_ = threadIdx.x; asm volatile("" : "+v"(tix_));
;   const int lane = tix_ & 63, wid = tix_ >> 6;
;   bft* lat = (bft*)(p.ws + OFF_LAT); const float* rt = (const float*)(p.ws + OFF_ROPE);
;   for (int it = blockIdx.x; it < T / 8; it += gridDim.x) {
;     int tok = it * 8 + wid; bft* r = lat + (size_t)tok * 704;
;     float q[6], kv[4], ss = 0, ss2 = 0;
;     for (int i = 0; i < 6; ++i) { q[i] = bf2f(r[lane + 64 * i]); ss += q[i] * q[i]; }
;     for (int i = 0; i < 4; ++i) { kv[i] = bf2f(r[384 + lane + 64 * i]); ss2 += kv[i] * kv[i]; }
;     float kr = bf2f(r[640 + lane]);
;     ...
;     int pos = tok_pos(tok); float c = rt[pos * 64 + (lane & 31)], s = rt[pos * 64 + 32 + (lane & 31)];
.LBB0_313:
	v_cndmask_b32_e64 v1, 0, 1, s[24:25]
	v_cmp_ne_u32_e64 s[0:1], 1, v1
	v_mov_b32_e32 v0, v180
	s_andn2_b64 vcc, exec, s[24:25]
	v_writelane_b32 v240, s0, 5
	s_nop 1
	v_writelane_b32 v240, s1, 6
	s_cbranch_vccnz .LBB0_316
	v_mbcnt_hi_u32_b32 v4, -1, v156
	v_and_b32_e32 v3, 64, v4
	v_add_u32_e32 v5, 64, v3
	v_xor_b32_e32 v3, 32, v4
	v_cmp_lt_i32_e32 vcc, v3, v5
	v_xor_b32_e32 v6, 16, v4
	v_xor_b32_e32 v7, 8, v4
	v_cndmask_b32_e32 v3, v4, v3, vcc
	v_cmp_lt_i32_e32 vcc, v6, v5
	s_load_dwordx2 s[4:5], s[88:89], 0x128
	v_xor_b32_e32 v8, 4, v4
	v_cndmask_b32_e32 v6, v4, v6, vcc
	v_cmp_lt_i32_e32 vcc, v7, v5
	v_xor_b32_e32 v9, 2, v4
	v_xor_b32_e32 v10, 1, v4
	v_cndmask_b32_e32 v7, v4, v7, vcc
	v_cmp_lt_i32_e32 vcc, v8, v5
	v_and_b32_e32 v1, 63, v0
	v_ashrrev_i32_e32 v2, 6, v0
	v_cndmask_b32_e32 v8, v4, v8, vcc
	v_cmp_lt_i32_e32 vcc, v9, v5
	s_waitcnt lgkmcnt(0)
	s_add_u32 s0, s4, 0x2bfc000
	s_addc_u32 s1, s5, 0
	v_cndmask_b32_e32 v9, v4, v9, vcc
	v_cmp_lt_i32_e32 vcc, v10, v5
	s_mov_b32 s6, 0x3b800000
	v_lshlrev_b32_e32 v3, 2, v3
	v_cndmask_b32_e32 v4, v4, v10, vcc
	v_lshlrev_b32_e32 v10, 2, v4
	v_and_b32_e32 v4, 31, v0
	v_cmp_gt_u32_e32 vcc, 32, v1
	v_lshlrev_b32_e32 v0, 1, v1
	v_mov_b32_e32 v1, 0
	v_lshl_add_u64 v[0:1], s[4:5], 0, v[0:1]
	s_mov_b64 s[4:5], 0xf9fc000
	v_lshlrev_b32_e32 v6, 2, v6
	v_lshlrev_b32_e32 v7, 2, v7
	v_lshlrev_b32_e32 v8, 2, v8
	v_lshlrev_b32_e32 v9, 2, v9
	v_lshl_add_u64 v[0:1], v[0:1], 0, s[4:5]
	v_add_u32_e32 v11, s85, v2
	s_lshl_b32 s3, s28, 3
	s_movk_i32 s4, 0x580
	s_mov_b32 s7, 0x3b2aaaab
	v_mov_b32_e32 v2, 0x358637bd
	s_mov_b32 s5, 0x800000
	s_movk_i32 s12, 0x7fff
	s_movk_i32 s13, 0x4000
	v_mov_b32_e32 v12, 0xfff
	v_mov_b32_e32 v13, 0x1fff
	v_lshlrev_b32_e32 v14, 2, v4
	s_mov_b32 s14, s86
	v_mad_i64_i32 v[234:235], s[8:9], v11, s4, v[0:1]
	global_load_ushort v220, v[234:235], off offset:384
	global_load_ushort v221, v[234:235], off offset:256
	global_load_ushort v222, v[234:235], off offset:640
	global_load_ushort v223, v[234:235], off offset:512
	global_load_ushort v224, v[234:235], off offset:896
	global_load_ushort v225, v[234:235], off offset:768
	global_load_ushort v226, v[234:235], off offset:1152
	global_load_ushort v227, v[234:235], off offset:1024
	global_load_ushort v228, v[234:235], off offset:128
	global_load_ushort v229, v[234:235], off
	global_load_ushort v230, v[234:235], off offset:1280
	v_cmp_gt_i32_e64 s[8:9], s13, v11
	s_nop 1
	v_cndmask_b32_e64 v233, v12, v13, s[8:9]
	v_and_b32_e32 v233, v233, v11
	v_lshl_or_b32 v233, v233, 8, v14
	global_load_dword v231, v233, s[0:1] offset:128
	global_load_dword v232, v233, s[0:1]
	v_add_u32_e32 v11, s3, v11
	s_waitcnt vmcnt(0)
.LBB0_315:
	s_waitcnt vmcnt(11)
	v_mov_b32_e32 v4, v234
	v_mov_b32_e32 v5, v235
	v_mov_b32_e32 v16, v220
	v_mov_b32_e32 v18, v221
	v_mov_b32_e32 v19, v222
	v_mov_b32_e32 v20, v223
	v_mov_b32_e32 v21, v224
	v_mov_b32_e32 v22, v225
	v_mov_b32_e32 v23, v226
	v_mov_b32_e32 v24, v227
	v_mov_b32_e32 v25, v228
	v_mov_b32_e32 v26, v229
	v_mov_b32_e32 v27, v230
	v_mov_b32_e32 v38, v231
	v_mov_b32_e32 v39, v232
	s_add_i32 s14, s14, s28
	s_cmpk_lt_i32 s14, 0x1800
	s_cbranch_scc0 .Lmla_nopf
	v_mad_i64_i32 v[234:235], s[8:9], v11, s4, v[0:1]
	global_load_ushort v220, v[234:235], off offset:384
	global_load_ushort v221, v[234:235], off offset:256
	global_load_ushort v222, v[234:235], off offset:640
	global_load_ushort v223, v[234:235], off offset:512
	global_load_ushort v224, v[234:235], off offset:896
	global_load_ushort v225, v[234:235], off offset:768
	global_load_ushort v226, v[234:235], off offset:1152
	global_load_ushort v227, v[234:235], off offset:1024
	global_load_ushort v228, v[234:235], off offset:128
	global_load_ushort v229, v[234:235], off
	global_load_ushort v230, v[234:235], off offset:1280
	v_cmp_gt_i32_e64 s[8:9], s13, v11
	s_nop 1
	v_cndmask_b32_e64 v233, v12, v13, s[8:9]
	v_and_b32_e32 v233, v233, v11
	v_lshl_or_b32 v233, v233, 8, v14
	global_load_dword v231, v233, s[0:1] offset:128
	global_load_dword v232, v233, s[0:1]
	v_add_u32_e32 v11, s3, v11
; DI bft f2bf(float x) { unsigned u = __float_as_uint(x); u += 0x7fffu + ((u >> 16) & 1u); return (bft)(u >> 16); }
; DI float bf2f(bft h) { return __uint_as_float(((unsigned)h) << 16); }
; DI float wave_sum(float v) { for (int o = 32; o > 0; o >>= 1) v += __shfl_xor(v, o); return v; }
; DI void phase_mlaprep(const Params& p) {
;     ...
;     for (int i = 0; i < 6; ++i) { q[i] = bf2f(r[lane + 64 * i]); ss += q[i] * q[i]; }
;     for (int i = 0; i < 4; ++i) { kv[i] = bf2f(r[384 + lane + 64 * i]); ss2 += kv[i] * kv[i]; }
;     float kr = bf2f(r[640 + lane]);
;     ss = wave_sum(ss); ss2 = wave_sum(ss2);
;     float rq = rsqrtf(ss * (1.f / 384) + EPS), rkv = rsqrtf(ss2 * (1.f / 256) + EPS);
;     for (int i = 0; i < 6; ++i) r[lane + 64 * i] = f2bf(q[i] * rq);
;     for (int i = 0; i < 4; ++i) r[384 + lane + 64 * i] = f2bf(kv[i] * rkv);
;     int pos = tok_pos(tok); float c = rt[pos * 64 + (lane & 31)], s = rt[pos * 64 + 32 + (lane & 31)];
;     float xo = __shfl_xor(kr, 32);
;     float o = lane < 32 ? kr * c - xo * s : xo * s + kr * c;
;     r[640 + lane] = f2bf(o);
.Lmla_nopf:
	v_lshlrev_b32_e32 v17, 16, v16
	v_lshlrev_b32_e32 v16, 16, v18
	v_lshlrev_b32_e32 v19, 16, v19
	v_lshlrev_b32_e32 v18, 16, v20
	v_lshlrev_b32_e32 v21, 16, v21
	v_lshlrev_b32_e32 v20, 16, v22
	v_lshlrev_b32_e32 v23, 16, v23
	v_lshlrev_b32_e32 v22, 16, v24
	v_lshlrev_b32_e32 v25, 16, v25
	v_lshlrev_b32_e32 v24, 16, v26
	v_lshlrev_b32_e32 v15, 16, v27
	v_pk_mul_f32 v[26:27], v[16:17], v[16:17]
	v_pk_mul_f32 v[28:29], v[18:19], v[18:19]
	v_mul_f32_e32 v26, v25, v25
	v_pk_mul_f32 v[32:33], v[22:23], v[22:23]
	v_pk_fma_f32 v[34:35], v[24:25], v[24:25], v[26:27] op_sel_hi:[1,1,0]
	v_pk_mul_f32 v[30:31], v[20:21], v[20:21]
	v_mov_b32_e32 v36, v32
	v_mov_b32_e32 v37, v28
	v_mov_b32_e32 v28, v33
	v_pk_fma_f32 v[32:33], v[16:17], v[16:17], v[34:35]
	v_mov_b32_e32 v26, v31
	v_mov_b32_e32 v31, v32
	v_pk_add_f32 v[26:27], v[30:31], v[26:27]
	ds_bpermute_b32 v40, v3, v15
	v_pk_add_f32 v[26:27], v[26:27], v[36:37]
	s_waitcnt lgkmcnt(0)
	v_mul_f32_e32 v30, v38, v40
	v_pk_add_f32 v[26:27], v[26:27], v[28:29]
	ds_bpermute_b32 v29, v3, v27
	ds_bpermute_b32 v28, v3, v26
	v_cndmask_b32_e64 v30, v30, -v30, vcc
	v_fmac_f32_e32 v30, v39, v15
	v_bfe_u32 v15, v30, 16, 1
	v_add3_u32 v15, v30, v15, s12
	s_waitcnt lgkmcnt(0)
	v_pk_add_f32 v[26:27], v[26:27], v[28:29]
	ds_bpermute_b32 v29, v6, v27
	ds_bpermute_b32 v28, v6, v26
	global_store_short_d16_hi v[4:5], v15, off offset:1280
	s_waitcnt lgkmcnt(0)
	v_pk_add_f32 v[26:27], v[26:27], v[28:29]
	ds_bpermute_b32 v29, v7, v27
	ds_bpermute_b32 v28, v7, v26
	s_waitcnt lgkmcnt(0)
	v_pk_add_f32 v[26:27], v[26:27], v[28:29]
	ds_bpermute_b32 v29, v8, v27
	ds_bpermute_b32 v28, v8, v26
	s_waitcnt lgkmcnt(0)
	v_pk_add_f32 v[26:27], v[26:27], v[28:29]
	ds_bpermute_b32 v29, v9, v27
	ds_bpermute_b32 v28, v9, v26
	s_waitcnt lgkmcnt(0)
	v_pk_add_f32 v[26:27], v[26:27], v[28:29]
	ds_bpermute_b32 v29, v10, v27
	ds_bpermute_b32 v28, v10, v26
	s_waitcnt lgkmcnt(0)
	v_pk_add_f32 v[26:27], v[26:27], v[28:29]
	s_nop 0
	v_pk_fma_f32 v[26:27], v[26:27], s[6:7], v[2:3] op_sel_hi:[1,1,0]
	s_nop 0
	v_mul_f32_e32 v15, 0x4b800000, v27
	v_cmp_gt_f32_e64 s[10:11], s5, v27
	v_mul_f32_e32 v28, 0x4b800000, v26
	v_cmp_gt_f32_e64 s[8:9], s5, v26
	v_cndmask_b32_e64 v15, v27, v15, s[10:11]
	v_rsq_f32_e32 v15, v15
	v_cndmask_b32_e64 v26, v26, v28, s[8:9]
	v_rsq_f32_e32 v26, v26
	v_mul_f32_e32 v27, 0x45800000, v15
	v_cndmask_b32_e64 v15, v15, v27, s[10:11]
	v_mul_f32_e32 v28, 0x45800000, v26
	v_cndmask_b32_e64 v26, v26, v28, s[8:9]
	v_mul_f32_e32 v24, v15, v24
	v_mul_f32_e32 v25, v15, v25
	v_mul_f32_e32 v16, v15, v16
	v_mul_f32_e32 v17, v15, v17
	v_mul_f32_e32 v18, v15, v18
	v_mul_f32_e32 v15, v15, v19
	v_mul_f32_e32 v19, v26, v20
	v_mul_f32_e32 v20, v26, v21
	v_mul_f32_e32 v21, v26, v22
	v_mul_f32_e32 v22, v26, v23
	v_bfe_u32 v23, v24, 16, 1
	v_bfe_u32 v26, v25, 16, 1
	v_bfe_u32 v27, v16, 16, 1
	v_bfe_u32 v28, v17, 16, 1
	v_bfe_u32 v29, v18, 16, 1
	v_bfe_u32 v30, v15, 16, 1
	v_bfe_u32 v31, v19, 16, 1
	v_bfe_u32 v32, v20, 16, 1
	v_bfe_u32 v33, v21, 16, 1
	v_bfe_u32 v34, v22, 16, 1
	v_add3_u32 v23, v24, v23, s12
	v_add3_u32 v24, v25, v26, s12
	v_add3_u32 v16, v16, v27, s12
	v_add3_u32 v17, v17, v28, s12
	v_add3_u32 v18, v18, v29, s12
	v_add3_u32 v15, v15, v30, s12
	v_add3_u32 v19, v19, v31, s12
	v_add3_u32 v20, v20, v32, s12
	v_add3_u32 v21, v21, v33, s12
	v_add3_u32 v22, v22, v34, s12
	global_store_short_d16_hi v[4:5], v23, off
	global_store_short_d16_hi v[4:5], v24, off offset:128
	global_store_short_d16_hi v[4:5], v16, off offset:256
	global_store_short_d16_hi v[4:5], v17, off offset:384
	global_store_short_d16_hi v[4:5], v18, off offset:512
	global_store_short_d16_hi v[4:5], v15, off offset:640
	global_store_short_d16_hi v[4:5], v19, off offset:768
	global_store_short_d16_hi v[4:5], v20, off offset:896
	global_store_short_d16_hi v[4:5], v21, off offset:1024
	global_store_short_d16_hi v[4:5], v22, off offset:1152
	s_cbranch_scc1 .LBB0_315
